# rg_scan pass 2 double-buffered (second register set, next 8 tokens' loads issued before processing the current 8)
# baseline (speedup 1.0000x reference)
; __device__ __forceinline__ unsigned cvt_pk_bf16(float lo, float hi) { const f32x2_t v = {lo, hi}; const bf16x2_t b = __builtin_convertvector(v, bf16x2_t); return __builtin_bit_cast(unsigned, b); }
; __device__ __forceinline__ float lo_bf(unsigned w) { return __uint_as_float(w << 16); }
; __device__ __forceinline__ float hi_bf(unsigned w) { return __uint_as_float(w & 0xffff0000u); }
; __device__ void rg_scan_phase(unsigned char* smem, const Params& p) {
;     ...
;         for (int i = 0; i < 128; ++i) { const unsigned l0 = *(const unsigned*)(la0 + (size_t)i * 512), v0 = *(const unsigned*)(u0 + (size_t)i * 512);
;             hfx = __expf(lo_bf(l0)) * hfx + lo_bf(v0); hfy = __expf(hi_bf(l0)) * hfy + hi_bf(v0); *(unsigned*)(hfp + (size_t)i * 512) = cvt_pk_bf16(hfx, hfy); }
.LBB0_178:
	s_or_b64 exec, exec, s[0:1]
	v_lshl_add_u64 v[4:5], s[6:7], 0, v[14:15]
	s_mov_b64 s[14:15], 0
	v_lshl_add_u64 v[6:7], v[4:5], 0, s[14:15]
	v_add_co_u32_e64 v18, s[0:1], s31, v6
	v_add_co_u32_e32 v16, vcc, 0x12c00000, v6
	s_nop 0
	v_addc_co_u32_e64 v19, s[0:1], 0, v7, s[0:1]
	v_add_co_u32_e64 v20, s[0:1], s34, v6
	v_addc_co_u32_e32 v17, vcc, 0, v7, vcc
	s_nop 0
	v_addc_co_u32_e64 v21, s[0:1], 0, v7, s[0:1]
	global_load_dword v22, v[18:19], off
	global_load_dword v23, v[20:21], off
	global_load_dword v24, v[18:19], off offset:1024
	global_load_dword v25, v[20:21], off offset:1024
	global_load_dword v26, v[18:19], off offset:2048
	global_load_dword v27, v[20:21], off offset:2048
	global_load_dword v28, v[20:21], off offset:3072
	global_load_dword v29, v[18:19], off offset:3072
	v_add_co_u32_e32 v18, vcc, 0x16c00000, v6
	global_load_dword v30, v[16:17], off
	global_load_dword v31, v[16:17], off offset:1024
	global_load_dword v38, v[16:17], off offset:2048
	v_addc_co_u32_e32 v19, vcc, 0, v7, vcc
	global_load_dword v39, v[18:19], off
	global_load_dword v40, v[18:19], off offset:1024
	global_load_dword v41, v[18:19], off offset:2048
	global_load_dword v42, v[18:19], off offset:3072
	global_load_dword v43, v[16:17], off offset:3072
	s_mov_b32 s16, 0x1ac00000
	v_add_co_u32_e32 v20, vcc, s16, v6
	s_mov_b32 s17, 0x1ac01000
	s_nop 0
	v_addc_co_u32_e32 v21, vcc, 0, v7, vcc
	v_add_co_u32_e32 v6, vcc, s17, v6
	s_nop 0
	v_addc_co_u32_e32 v7, vcc, 0, v7, vcc
	s_add_u32 s14, s14, 0x2000
	s_addc_u32 s15, s15, 0
.LBB0_179:
	v_lshl_add_u64 v[70:71], v[4:5], 0, s[14:15]
	v_add_co_u32_e64 v82, s[0:1], s31, v70
	v_add_co_u32_e32 v80, vcc, 0x12c00000, v70
	s_nop 0
	v_addc_co_u32_e64 v83, s[0:1], 0, v71, s[0:1]
	v_add_co_u32_e64 v84, s[0:1], s34, v70
	v_addc_co_u32_e32 v81, vcc, 0, v71, vcc
	s_nop 0
	v_addc_co_u32_e64 v85, s[0:1], 0, v71, s[0:1]
	global_load_dword v86, v[82:83], off
	global_load_dword v87, v[84:85], off
	global_load_dword v88, v[82:83], off offset:1024
	global_load_dword v89, v[84:85], off offset:1024
	global_load_dword v90, v[82:83], off offset:2048
	global_load_dword v91, v[84:85], off offset:2048
	global_load_dword v92, v[84:85], off offset:3072
	global_load_dword v93, v[82:83], off offset:3072
	v_add_co_u32_e32 v82, vcc, 0x16c00000, v70
	global_load_dword v94, v[80:81], off
	global_load_dword v95, v[80:81], off offset:1024
	global_load_dword v102, v[80:81], off offset:2048
	v_addc_co_u32_e32 v83, vcc, 0, v71, vcc
	global_load_dword v103, v[82:83], off
	global_load_dword v104, v[82:83], off offset:1024
	global_load_dword v105, v[82:83], off offset:2048
	global_load_dword v106, v[82:83], off offset:3072
	global_load_dword v107, v[80:81], off offset:3072
	s_mov_b32 s16, 0x1ac00000
	v_add_co_u32_e32 v84, vcc, s16, v70
	s_mov_b32 s17, 0x1ac01000
	s_nop 0
	v_addc_co_u32_e32 v85, vcc, 0, v71, vcc
	v_add_co_u32_e32 v70, vcc, s17, v70
	s_nop 0
	v_addc_co_u32_e32 v71, vcc, 0, v71, vcc
	s_add_u32 s14, s14, 0x2000
	s_addc_u32 s15, s15, 0
	s_waitcnt vmcnt(31)
	v_lshlrev_b32_e32 v44, 16, v22
	s_waitcnt vmcnt(30)
	v_lshlrev_b32_e32 v16, 16, v23
	s_waitcnt vmcnt(29)
	v_lshlrev_b32_e32 v46, 16, v24
	s_waitcnt vmcnt(28)
	v_lshlrev_b32_e32 v18, 16, v25
	v_and_b32_e32 v47, 0xffff0000, v24
	v_and_b32_e32 v19, 0xffff0000, v25
	s_waitcnt vmcnt(27)
	v_lshlrev_b32_e32 v48, 16, v26
	s_waitcnt vmcnt(25)
	v_lshlrev_b32_e32 v24, 16, v28
	v_and_b32_e32 v25, 0xffff0000, v28
	s_waitcnt vmcnt(23)
	v_lshlrev_b32_e32 v28, 16, v30
	v_and_b32_e32 v30, 0xffff0000, v30
	v_and_b32_e32 v45, 0xffff0000, v22
	v_and_b32_e32 v17, 0xffff0000, v23
	v_lshlrev_b32_e32 v22, 16, v27
	v_and_b32_e32 v26, 0xffff0000, v26
	v_and_b32_e32 v23, 0xffff0000, v27
	v_lshlrev_b32_e32 v27, 16, v29
	v_and_b32_e32 v29, 0xffff0000, v29
	s_waitcnt vmcnt(22)
	v_lshlrev_b32_e32 v49, 16, v31
	v_and_b32_e32 v31, 0xffff0000, v31
	v_mul_f32_e32 v44, 0x3fb8aa3b, v44
	v_mul_f32_e32 v48, 0x3fb8aa3b, v48
	v_mul_f32_e32 v54, 0x3fb8aa3b, v28
	v_mul_f32_e32 v55, 0x3fb8aa3b, v30
	s_waitcnt vmcnt(21)
	v_lshlrev_b32_e32 v50, 16, v38
	v_and_b32_e32 v38, 0xffff0000, v38
	v_mul_f32_e32 v45, 0x3fb8aa3b, v45
	v_mul_f32_e32 v51, 0x3fb8aa3b, v26
	v_mul_f32_e32 v53, 0x3fb8aa3b, v29
	v_mul_f32_e32 v56, 0x3fb8aa3b, v49
	s_waitcnt vmcnt(19)
	v_lshlrev_b32_e32 v28, 16, v40
	v_mul_f32_e32 v57, 0x3fb8aa3b, v31
	v_and_b32_e32 v29, 0xffff0000, v40
	v_exp_f32_e32 v40, v44
	v_exp_f32_e32 v44, v48
	v_exp_f32_e32 v48, v54
	v_exp_f32_e32 v49, v55
	v_mul_f32_e32 v46, 0x3fb8aa3b, v46
	v_mul_f32_e32 v47, 0x3fb8aa3b, v47
	v_mul_f32_e32 v52, 0x3fb8aa3b, v27
	v_mul_f32_e32 v58, 0x3fb8aa3b, v50
	s_waitcnt vmcnt(18)
	v_lshlrev_b32_e32 v30, 16, v41
	v_mul_f32_e32 v59, 0x3fb8aa3b, v38
	v_and_b32_e32 v31, 0xffff0000, v41
	s_waitcnt vmcnt(16)
; __device__ __forceinline__ unsigned cvt_pk_bf16(float lo, float hi) { const f32x2_t v = {lo, hi}; const bf16x2_t b = __builtin_convertvector(v, bf16x2_t); return __builtin_bit_cast(unsigned, b); }
; __device__ __forceinline__ float lo_bf(unsigned w) { return __uint_as_float(w << 16); }
; __device__ __forceinline__ float hi_bf(unsigned w) { return __uint_as_float(w & 0xffff0000u); }
; __device__ void rg_scan_phase(unsigned char* smem, const Params& p) {
;     ...
;         for (int i = 0; i < 128; ++i) { const unsigned l0 = *(const unsigned*)(la0 + (size_t)i * 512), v0 = *(const unsigned*)(u0 + (size_t)i * 512);
;             hfx = __expf(lo_bf(l0)) * hfx + lo_bf(v0); hfy = __expf(hi_bf(l0)) * hfy + hi_bf(v0); *(unsigned*)(hfp + (size_t)i * 512) = cvt_pk_bf16(hfx, hfy); }
	v_lshlrev_b32_e32 v60, 16, v43
	v_and_b32_e32 v61, 0xffff0000, v43
	v_exp_f32_e32 v41, v45
	v_exp_f32_e32 v45, v51
	v_exp_f32_e32 v50, v56
	v_exp_f32_e32 v51, v57
	v_lshlrev_b32_e32 v26, 16, v39
	v_and_b32_e32 v27, 0xffff0000, v39
	v_lshlrev_b32_e32 v38, 16, v42
	v_and_b32_e32 v39, 0xffff0000, v42
	v_exp_f32_e32 v42, v46
	v_exp_f32_e32 v43, v47
	v_exp_f32_e32 v46, v52
	v_exp_f32_e32 v47, v53
	v_exp_f32_e32 v52, v58
	v_exp_f32_e32 v53, v59
	v_mul_f32_e32 v54, 0x3fb8aa3b, v60
	v_mul_f32_e32 v55, 0x3fb8aa3b, v61
	v_exp_f32_e32 v54, v54
	v_exp_f32_e32 v55, v55
	v_pk_fma_f32 v[2:3], v[2:3], v[48:49], v[26:27]
	s_nop 0
	v_cvt_pk_bf16_f32 v26, v2, v3
	v_pk_fma_f32 v[2:3], v[2:3], v[50:51], v[28:29]
	global_store_dword v[6:7], v26, off offset:-4096
	v_cvt_pk_bf16_f32 v26, v2, v3
	v_pk_fma_f32 v[2:3], v[2:3], v[52:53], v[30:31]
	global_store_dword v[20:21], v26, off offset:1024
	v_cvt_pk_bf16_f32 v26, v2, v3
	v_pk_fma_f32 v[2:3], v[2:3], v[54:55], v[38:39]
	global_store_dword v[20:21], v26, off offset:2048
	v_cvt_pk_bf16_f32 v26, v2, v3
	v_pk_fma_f32 v[2:3], v[2:3], v[40:41], v[16:17]
	global_store_dword v[20:21], v26, off offset:3072
	v_cvt_pk_bf16_f32 v16, v2, v3
	v_pk_fma_f32 v[2:3], v[2:3], v[42:43], v[18:19]
	global_store_dword v[6:7], v16, off
	v_cvt_pk_bf16_f32 v16, v2, v3
	v_pk_fma_f32 v[2:3], v[2:3], v[44:45], v[22:23]
	global_store_dword v[6:7], v16, off offset:1024
	v_cvt_pk_bf16_f32 v16, v2, v3
	v_pk_fma_f32 v[2:3], v[2:3], v[46:47], v[24:25]
	global_store_dword v[6:7], v16, off offset:2048
	v_cvt_pk_bf16_f32 v16, v2, v3
	global_store_dword v[6:7], v16, off offset:3072
	v_lshl_add_u64 v[6:7], v[4:5], 0, s[14:15]
	v_add_co_u32_e64 v18, s[0:1], s31, v6
	v_add_co_u32_e32 v16, vcc, 0x12c00000, v6
	s_nop 0
	v_addc_co_u32_e64 v19, s[0:1], 0, v7, s[0:1]
	v_add_co_u32_e64 v20, s[0:1], s34, v6
	v_addc_co_u32_e32 v17, vcc, 0, v7, vcc
	s_nop 0
	v_addc_co_u32_e64 v21, s[0:1], 0, v7, s[0:1]
	global_load_dword v22, v[18:19], off
	global_load_dword v23, v[20:21], off
	global_load_dword v24, v[18:19], off offset:1024
	global_load_dword v25, v[20:21], off offset:1024
	global_load_dword v26, v[18:19], off offset:2048
	global_load_dword v27, v[20:21], off offset:2048
	global_load_dword v28, v[20:21], off offset:3072
	global_load_dword v29, v[18:19], off offset:3072
	v_add_co_u32_e32 v18, vcc, 0x16c00000, v6
	global_load_dword v30, v[16:17], off
	global_load_dword v31, v[16:17], off offset:1024
	global_load_dword v38, v[16:17], off offset:2048
	v_addc_co_u32_e32 v19, vcc, 0, v7, vcc
	global_load_dword v39, v[18:19], off
	global_load_dword v40, v[18:19], off offset:1024
	global_load_dword v41, v[18:19], off offset:2048
	global_load_dword v42, v[18:19], off offset:3072
	global_load_dword v43, v[16:17], off offset:3072
	s_mov_b32 s16, 0x1ac00000
	v_add_co_u32_e32 v20, vcc, s16, v6
	s_mov_b32 s17, 0x1ac01000
	s_nop 0
	v_addc_co_u32_e32 v21, vcc, 0, v7, vcc
	v_add_co_u32_e32 v6, vcc, s17, v6
	s_nop 0
	v_addc_co_u32_e32 v7, vcc, 0, v7, vcc
	s_add_u32 s14, s14, 0x2000
	s_addc_u32 s15, s15, 0
	s_waitcnt vmcnt(39)
	v_lshlrev_b32_e32 v108, 16, v86
	s_waitcnt vmcnt(38)
	v_lshlrev_b32_e32 v80, 16, v87
	s_waitcnt vmcnt(37)
	v_lshlrev_b32_e32 v110, 16, v88
	s_waitcnt vmcnt(36)
	v_lshlrev_b32_e32 v82, 16, v89
	v_and_b32_e32 v111, 0xffff0000, v88
	v_and_b32_e32 v83, 0xffff0000, v89
	s_waitcnt vmcnt(35)
	v_lshlrev_b32_e32 v112, 16, v90
	s_waitcnt vmcnt(33)
	v_lshlrev_b32_e32 v88, 16, v92
	v_and_b32_e32 v89, 0xffff0000, v92
	s_waitcnt vmcnt(31)
	v_lshlrev_b32_e32 v92, 16, v94
	v_and_b32_e32 v94, 0xffff0000, v94
	v_and_b32_e32 v109, 0xffff0000, v86
	v_and_b32_e32 v81, 0xffff0000, v87
	v_lshlrev_b32_e32 v86, 16, v91
	v_and_b32_e32 v90, 0xffff0000, v90
	v_and_b32_e32 v87, 0xffff0000, v91
	v_lshlrev_b32_e32 v91, 16, v93
	v_and_b32_e32 v93, 0xffff0000, v93
	s_waitcnt vmcnt(30)
	v_lshlrev_b32_e32 v113, 16, v95
	v_and_b32_e32 v95, 0xffff0000, v95
	v_mul_f32_e32 v108, 0x3fb8aa3b, v108
	v_mul_f32_e32 v112, 0x3fb8aa3b, v112
	v_mul_f32_e32 v118, 0x3fb8aa3b, v92
	v_mul_f32_e32 v119, 0x3fb8aa3b, v94
	s_waitcnt vmcnt(29)
	v_lshlrev_b32_e32 v114, 16, v102
	v_and_b32_e32 v102, 0xffff0000, v102
	v_mul_f32_e32 v109, 0x3fb8aa3b, v109
	v_mul_f32_e32 v115, 0x3fb8aa3b, v90
	v_mul_f32_e32 v117, 0x3fb8aa3b, v93
	v_mul_f32_e32 v120, 0x3fb8aa3b, v113
	s_waitcnt vmcnt(27)
	v_lshlrev_b32_e32 v92, 16, v104
	v_mul_f32_e32 v121, 0x3fb8aa3b, v95
	v_and_b32_e32 v93, 0xffff0000, v104
	v_exp_f32_e32 v104, v108
	v_exp_f32_e32 v108, v112
	v_exp_f32_e32 v112, v118
	v_exp_f32_e32 v113, v119
	v_mul_f32_e32 v110, 0x3fb8aa3b, v110
	v_mul_f32_e32 v111, 0x3fb8aa3b, v111
	v_mul_f32_e32 v116, 0x3fb8aa3b, v91
	v_mul_f32_e32 v122, 0x3fb8aa3b, v114
	s_waitcnt vmcnt(26)
	v_lshlrev_b32_e32 v94, 16, v105
	v_mul_f32_e32 v123, 0x3fb8aa3b, v102
	v_and_b32_e32 v95, 0xffff0000, v105
	s_waitcnt vmcnt(24)
	v_lshlrev_b32_e32 v124, 16, v107
	v_and_b32_e32 v125, 0xffff0000, v107
	v_exp_f32_e32 v105, v109
	v_exp_f32_e32 v109, v115
	v_exp_f32_e32 v114, v120
	v_exp_f32_e32 v115, v121
	v_lshlrev_b32_e32 v90, 16, v103
	v_and_b32_e32 v91, 0xffff0000, v103
	v_lshlrev_b32_e32 v102, 16, v106
	v_and_b32_e32 v103, 0xffff0000, v106
	v_exp_f32_e32 v106, v110
	v_exp_f32_e32 v107, v111
	v_exp_f32_e32 v110, v116
	v_exp_f32_e32 v111, v117
	v_exp_f32_e32 v116, v122
	v_exp_f32_e32 v117, v123
	v_mul_f32_e32 v118, 0x3fb8aa3b, v124
	v_mul_f32_e32 v119, 0x3fb8aa3b, v125
	v_exp_f32_e32 v118, v118
	v_exp_f32_e32 v119, v119
	v_pk_fma_f32 v[2:3], v[2:3], v[112:113], v[90:91]
	s_nop 0
	v_cvt_pk_bf16_f32 v90, v2, v3
	v_pk_fma_f32 v[2:3], v[2:3], v[114:115], v[92:93]
	global_store_dword v[70:71], v90, off offset:-4096
	v_cvt_pk_bf16_f32 v90, v2, v3
	v_pk_fma_f32 v[2:3], v[2:3], v[116:117], v[94:95]
	global_store_dword v[84:85], v90, off offset:1024
	v_cvt_pk_bf16_f32 v90, v2, v3
	v_pk_fma_f32 v[2:3], v[2:3], v[118:119], v[102:103]
	global_store_dword v[84:85], v90, off offset:2048
	v_cvt_pk_bf16_f32 v90, v2, v3
	v_pk_fma_f32 v[2:3], v[2:3], v[104:105], v[80:81]
	global_store_dword v[84:85], v90, off offset:3072
	v_cvt_pk_bf16_f32 v80, v2, v3
	v_pk_fma_f32 v[2:3], v[2:3], v[106:107], v[82:83]
	global_store_dword v[70:71], v80, off
	v_cvt_pk_bf16_f32 v80, v2, v3
	v_pk_fma_f32 v[2:3], v[2:3], v[108:109], v[86:87]
	global_store_dword v[70:71], v80, off offset:1024
	v_cvt_pk_bf16_f32 v80, v2, v3
	v_pk_fma_f32 v[2:3], v[2:3], v[110:111], v[88:89]
	global_store_dword v[70:71], v80, off offset:2048
	v_cvt_pk_bf16_f32 v80, v2, v3
	global_store_dword v[70:71], v80, off offset:3072
	s_cmp_eq_u32 s14, 0x22000
	s_cbranch_scc0 .LBB0_179
; __device__ void rg_scan_phase(unsigned char* smem, const Params& p) {
;     ...
;         const bf16_t* gp = urg + ((size_t)b * SEQ + seg * 128) * 1024 + 512 + j; bf16_t* yo = yc + ((size_t)b * SEQ + seg * 128) * 1536 + 1024 + j;
; #pragma unroll 8
;         for (int i = 0; i < 128; ++i) { const int tt = 127 - i; const unsigned l1 = *(const unsigned*)(la1 + (size_t)tt * 512), v1 = *(const unsigned*)(u1 + (size_t)tt * 512);
	s_waitcnt vmcnt(0)
	v_mov_b32_e32 v2, 0x600000
	v_mad_i64_i32 v[2:3], s[0:1], s12, v2, v[10:11]
	s_lshl_b64 s[0:1], s[12:13], 22
	v_lshlrev_b32_e32 v184, 1, v184
	v_lshl_add_u64 v[4:5], v[12:13], 0, s[0:1]
	s_movk_i32 s36, 0xe000
	v_lshl_add_u64 v[2:3], v[2:3], 0, v[184:185]
	v_lshl_add_u64 v[4:5], v[4:5], 0, v[184:185]
	s_movk_i32 s12, 0x80
	s_mov_b32 s37, -1
	v_lshl_add_u64 v[90:91], s[6:7], 0, v[14:15]
	s_mov_b32 s0, 0x14c1fc00
	s_mov_b32 s1, 0
	v_lshl_add_u64 v[38:39], v[90:91], 0, s[0:1]
	s_mov_b32 s0, 0x18c1fc00
	v_lshl_add_u64 v[56:57], v[90:91], 0, s[0:1]
	s_mov_b32 s0, 0x1ac1fc00
	v_lshl_add_u64 v[58:59], v[90:91], 0, s[0:1]
	v_lshl_add_u64 v[60:61], s[6:7], 0, v[4:5]
	s_mov_b32 s0, 0xdc3fc00
	v_lshl_add_u64 v[60:61], v[60:61], 0, s[0:1]
	s_mov_b32 s14, 0xfffff000
	s_mov_b32 s15, -1
	global_load_dword v16, v[38:39], off
	global_load_dword v17, v[56:57], off
	global_load_dword v18, v[60:61], off
	global_load_dword v19, v[58:59], off
	global_load_dword v20, v[38:39], off offset:-1024
	global_load_dword v21, v[56:57], off offset:-1024
	global_load_dword v22, v[60:61], off offset:-2048
	global_load_dword v23, v[58:59], off offset:-1024
	v_lshl_add_u64 v[60:61], v[60:61], 0, s[14:15]
	global_load_dword v24, v[38:39], off offset:-2048
	global_load_dword v25, v[56:57], off offset:-2048
	global_load_dword v26, v[60:61], off
	global_load_dword v27, v[58:59], off offset:-2048
	global_load_dword v28, v[38:39], off offset:-3072
	global_load_dword v29, v[56:57], off offset:-3072
	global_load_dword v30, v[60:61], off offset:-2048
	global_load_dword v31, v[58:59], off offset:-3072
	v_lshl_add_u64 v[38:39], v[38:39], 0, s[14:15]
	v_lshl_add_u64 v[56:57], v[56:57], 0, s[14:15]
	v_lshl_add_u64 v[58:59], v[58:59], 0, s[14:15]
	v_lshl_add_u64 v[60:61], v[60:61], 0, s[14:15]
	global_load_dword v40, v[38:39], off
	global_load_dword v41, v[56:57], off
	global_load_dword v42, v[60:61], off
	global_load_dword v43, v[58:59], off
	global_load_dword v44, v[38:39], off offset:-1024
	global_load_dword v45, v[56:57], off offset:-1024
	global_load_dword v46, v[60:61], off offset:-2048
	global_load_dword v47, v[58:59], off offset:-1024
	v_lshl_add_u64 v[60:61], v[60:61], 0, s[14:15]
	global_load_dword v48, v[38:39], off offset:-2048
	global_load_dword v49, v[56:57], off offset:-2048
	global_load_dword v50, v[60:61], off
	global_load_dword v51, v[58:59], off offset:-2048
	global_load_dword v52, v[38:39], off offset:-3072
	global_load_dword v53, v[56:57], off offset:-3072
	global_load_dword v54, v[60:61], off offset:-2048
	global_load_dword v55, v[58:59], off offset:-3072
	v_lshl_add_u64 v[14:15], v[14:15], 0, s[36:37]
	s_movk_i32 s14, 0xc000
	v_lshl_add_u64 v[4:5], v[4:5], 0, s[14:15]
